# attn DMA issue moved to loop bottom; FFN-in k-loop rotated (last 4 MFMA groups after next barrier, DMA interleaved); static setprio 1 waves 4-7
# speedup vs baseline: 1.0173x; 1.0173x over previous
; #define LAS __attribute__((address_space(3)))
; __global__ void __launch_bounds__(512) mega(Params p) {
;     extern __shared__ __attribute__((aligned(16))) char lds[];
;     cg::grid_group grid = cg::this_grid();
;     const int tid = threadIdx.x, wid = tid >> 6, lane = tid & 63;
;     char* ws = p.ws;
;     if (tid < 4) ((volatile LAS unsigned*)((LAS char*)lds + XB_LDS_OFF))[tid] = 0u;
;     __syncthreads();
;     (void)xcd_barrier_post((unsigned*)(ws + OFF_BAR), (volatile LAS unsigned*)((LAS char*)lds + XB_LDS_OFF));
_Z4mega6Params:
	s_load_dwordx2 s[28:29], s[0:1], 0x138
	s_load_dwordx2 s[68:69], s[0:1], 0xb0
	s_add_u32 s52, s0, 0x138
	v_writelane_b32 v254, s0, 0
	v_and_b32_e32 v168, 0x3ff, v0
	s_addc_u32 s53, s1, 0
	v_readfirstlane_b32 s4, v0
	s_nop 3
	s_and_b32 s4, s4, 0x3ff
	s_lshr_b32 s4, s4, 6
	s_cmp_ge_u32 s4, 4
	s_cbranch_scc0 .Lprio_done
	s_setprio 1
.Lprio_done:
	v_writelane_b32 v254, s1, 1
	v_cmp_gt_u32_e32 vcc, 4, v168
	s_and_saveexec_b64 s[4:5], vcc
	v_lshl_add_u32 v1, v168, 2, 0
	v_add_u32_e32 v1, 0x21400, v1
	v_mov_b32_e32 v2, 0
	ds_write_b32 v1, v2
	s_or_b64 exec, exec, s[4:5]
	v_cmp_eq_u32_e64 s[0:1], 0, v168
	s_waitcnt lgkmcnt(0)
	s_barrier
	v_writelane_b32 v254, s0, 2
	s_getreg_b32 s3, hwreg(HW_REG_XCC_ID, 0, 4)
	s_mov_b32 s11, 0
	v_writelane_b32 v254, s1, 3
	s_and_saveexec_b64 s[4:5], s[0:1]
	s_cbranch_execz .LBB0_5
	s_mov_b64 s[6:7], exec
	v_mbcnt_lo_u32_b32 v1, s6, 0
	v_mbcnt_hi_u32_b32 v1, s7, v1
	v_cmp_eq_u32_e32 vcc, 0, v1
	s_and_b64 s[8:9], exec, vcc
	s_mov_b64 exec, s[8:9]
	s_cbranch_execz .LBB0_5
	s_lshl_b32 s3, s3, 8
	s_and_b32 s3, s3, 0xf00
	s_add_u32 s8, s68, s3
	s_addc_u32 s9, s69, 0
	s_bcnt1_i32_b64 s3, s[6:7]
	v_mov_b32_e32 v1, 0x38f80000
	v_mov_b32_e32 v2, s3
	global_atomic_add v1, v2, s[8:9] offset:1024

; #define MFMA(a, b, c) __builtin_amdgcn_mfma_f32_32x32x16_bf16((a), (b), (c), 0, 0, 0)
; DI bf16x8 ldfrag(const char* lds, int row, int chunk) { return *(const bf16x8*)(lds + swz(row, chunk)); }
; DI void attn_phase(const bf16_t* __restrict__ qb, const bf16_t* __restrict__ kb, const bf16_t* __restrict__ vt, bf16_t* __restrict__ ob, ...
;     ...
;             float ps = 0.f;
;             bf16x8 pq[4];
;     ...
;             ATT_SOFTQ(0);
; #pragma unroll
;             for (int q = 0; q < 4; ++q) {
;                 if (q < 3) {
; #pragma unroll
;                     for (int ef = 0; ef < 4; ++ef) vf[(q + 1) & 1][ef] = ldfrag(vl, ef * 32 + l31, ((q + 1) >> 1) * 4 + 2 * ((q + 1) & 1) + hh);
;                     if (q == 0) ATT_SOFTQ(1); else if (q == 1) ATT_SOFTQ(2); else ATT_SOFTQ(3);
;                 }
; #pragma unroll
;                 for (int ef = 0; ef < 4; ++ef) oacc[ef] = MFMA(vf[q & 1][ef], pq[q], oacc[ef]);
;             }
;             l_run += ps;
;             __builtin_amdgcn_sched_group_barrier(0x002, 20, 0);
; #pragma unroll
;             for (int g_ = 0; g_ < 12; ++g_) { __builtin_amdgcn_sched_group_barrier(0x008, 1, 0); __builtin_amdgcn_sched_group_barrier(0x100, 1, 0); __builtin_amdgcn_sched_group_barrier(0x002, 5, 0); }
;             __builtin_amdgcn_sched_group_barrier(0x008, 4, 0);
;         }
.LBB0_214:
	v_exp_f32_e32 v65, v98
	v_exp_f32_e32 v98, v99
	v_exp_f32_e32 v99, v100
	v_exp_f32_e32 v100, v101
	v_add_f32_e32 v101, 0, v65
	v_exp_f32_e32 v102, v102
	v_add_f32_e32 v101, v98, v101
	v_exp_f32_e32 v103, v103
	v_add_f32_e32 v101, v99, v101
	v_exp_f32_e32 v104, v104
	v_add_f32_e32 v101, v100, v101
	v_exp_f32_e32 v105, v105
	v_add_f32_e32 v101, v102, v101
	v_exp_f32_e32 v106, v106
	v_exp_f32_e32 v107, v107
	v_add_f32_e32 v101, v103, v101
	v_add_f32_e32 v101, v104, v101
	v_exp_f32_e32 v159, v108
	v_exp_f32_e32 v161, v109
	v_exp_f32_e32 v110, v110
	v_exp_f32_e32 v111, v111
	v_exp_f32_e32 v112, v112
	v_exp_f32_e32 v172, v113
	v_add_f32_e32 v146, v105, v101
	v_cvt_pk_bf16_f32 v98, v65, v98
	v_cvt_pk_bf16_f32 v99, v99, v100
	v_cvt_pk_bf16_f32 v100, v102, v103
	v_add_u32_e32 v65, s17, v193
	v_cvt_pk_bf16_f32 v102, v106, v107
	v_add_f32_e32 v106, v106, v146
	v_cvt_pk_bf16_f32 v101, v104, v105
	v_add_u32_e32 v157, v65, v198
	v_add_f32_e32 v113, v107, v106
	v_cvt_pk_bf16_f32 v103, v159, v161
	v_cvt_pk_bf16_f32 v104, v110, v111
	v_cvt_pk_bf16_f32 v105, v112, v172
	s_waitcnt lgkmcnt(0)
	v_mfma_f32_32x32x16_bf16 v[0:15], v[142:145], v[98:101], v[0:15]
	ds_read_b128 v[106:109], v157 offset:16384
	v_add_f32_e32 v113, v159, v113
	v_add_f32_e32 v113, v161, v113
	v_add_f32_e32 v110, v110, v113
	v_add_f32_e32 v110, v111, v110
	v_add_f32_e32 v142, v112, v110
	v_exp_f32_e32 v143, v86
	v_mfma_f32_32x32x16_bf16 v[16:31], v[138:141], v[98:101], v[16:31]
	ds_read_b128 v[110:113], v157 offset:20480
	v_add_f32_e32 v138, v172, v142
	v_exp_f32_e32 v139, v82
	v_exp_f32_e32 v140, v83
	v_exp_f32_e32 v141, v84
	v_exp_f32_e32 v142, v85
	v_exp_f32_e32 v144, v87
	v_add_u32_e32 v145, v65, v199
	v_cvt_pk_bf16_f32 v82, v139, v140
	v_cvt_pk_bf16_f32 v83, v141, v142
	v_cvt_pk_bf16_f32 v84, v143, v144
	v_mfma_f32_32x32x16_bf16 v[32:47], v[134:137], v[98:101], v[32:47]
	v_exp_f32_e32 v134, v88
	v_exp_f32_e32 v135, v89
	ds_read_b128 v[86:89], v157 offset:24576
	v_add_f32_e32 v136, v139, v138
	v_add_f32_e32 v136, v140, v136
	v_add_f32_e32 v136, v141, v136
	v_add_f32_e32 v136, v142, v136
	v_cvt_pk_bf16_f32 v85, v134, v135
	v_mfma_f32_32x32x16_bf16 v[48:63], v[130:133], v[98:101], v[48:63]
	ds_read_b128 v[98:101], v157 offset:28672
	v_add_f32_e32 v130, v143, v136
	v_add_f32_e32 v130, v144, v130
	v_add_f32_e32 v130, v134, v130
	v_exp_f32_e32 v131, v90
	v_add_f32_e32 v130, v135, v130
	v_exp_f32_e32 v132, v91
	v_exp_f32_e32 v133, v92
	v_exp_f32_e32 v134, v93
	v_exp_f32_e32 v135, v94
	v_exp_f32_e32 v136, v95
	v_exp_f32_e32 v137, v96
	v_exp_f32_e32 v138, v97
	v_add_u32_e32 v65, v65, v200
	s_waitcnt lgkmcnt(0)
	v_mfma_f32_32x32x16_bf16 v[0:15], v[106:109], v[102:105], v[0:15]
	ds_read_b128 v[106:109], v145 offset:16384
	v_add_f32_e32 v130, v131, v130
	v_cvt_pk_bf16_f32 v90, v131, v132
	v_cvt_pk_bf16_f32 v91, v133, v134
	v_cvt_pk_bf16_f32 v92, v135, v136
	v_cvt_pk_bf16_f32 v93, v137, v138
	s_add_i32 s18, s18, 1
	v_mfma_f32_32x32x16_bf16 v[16:31], v[110:113], v[102:105], v[16:31]
	ds_read_b128 v[94:97], v145 offset:20480
	v_add_f32_e32 v110, v132, v130
	v_add_f32_e32 v110, v133, v110
	v_add_f32_e32 v110, v134, v110
	v_add_f32_e32 v110, v135, v110
	v_add_f32_e32 v110, v136, v110
	s_add_i32 s19, s19, 0x8000
	v_mfma_f32_32x32x16_bf16 v[32:47], v[86:89], v[102:105], v[32:47]
	ds_read_b128 v[86:89], v145 offset:24576
	v_add_f32_e32 v110, v137, v110
	v_add_f32_e32 v110, v138, v110
	v_add_f32_e32 v64, v64, v110
	v_mfma_f32_32x32x16_bf16 v[48:63], v[98:101], v[102:105], v[48:63]
	ds_read_b128 v[98:101], v145 offset:28672
	s_waitcnt lgkmcnt(0)
	v_mfma_f32_32x32x16_bf16 v[0:15], v[106:109], v[82:85], v[0:15]
	ds_read_b128 v[102:105], v65 offset:16384
	v_mfma_f32_32x32x16_bf16 v[16:31], v[94:97], v[82:85], v[16:31]
	ds_read_b128 v[94:97], v65 offset:20480
	v_mfma_f32_32x32x16_bf16 v[32:47], v[86:89], v[82:85], v[32:47]
	ds_read_b128 v[86:89], v65 offset:24576
	v_mfma_f32_32x32x16_bf16 v[48:63], v[98:101], v[82:85], v[48:63]
	ds_read_b128 v[82:85], v65 offset:28672
	s_waitcnt lgkmcnt(0)
	v_mfma_f32_32x32x16_bf16 v[0:15], v[102:105], v[90:93], v[0:15]
	v_mfma_f32_32x32x16_bf16 v[16:31], v[94:97], v[90:93], v[16:31]
	v_mfma_f32_32x32x16_bf16 v[32:47], v[86:89], v[90:93], v[32:47]
	v_mfma_f32_32x32x16_bf16 v[48:63], v[82:85], v[90:93], v[48:63]
	s_add_i32 s17, s18, 3
	s_min_u32 s86, s17, s9
	s_add_i32 s17, s19, 0xffff8000
	s_and_b32 s17, s17, 0x18000
	s_add_i32 s38, s30, s17
	s_lshl_b64 s[20:21], s[86:87], 17
	v_lshl_add_u64 v[82:83], v[164:165], 0, s[20:21]
	s_mov_b32 m0, s38
	s_lshl_b32 s86, s86, 7
	global_load_lds_dwordx4 v[82:83], off
	v_lshl_add_u64 v[82:83], v[82:83], 0, s[14:15]
	s_add_i32 m0, s38, 0x2000
	v_lshl_add_u64 v[84:85], v[166:167], 0, s[86:87]
	global_load_lds_dwordx4 v[82:83], off
	s_add_i32 m0, s38, 0x4000
	s_mov_b32 s17, s87
	global_load_lds_dwordx4 v[84:85], off
	v_lshl_add_u64 v[82:83], v[84:85], 0, s[16:17]
	s_add_i32 m0, s38, 0x6000
	s_cmp_eq_u32 s9, s18
	global_load_lds_dwordx4 v[82:83], off
	s_cbranch_scc1 .LBB0_217
; DI void attn_phase(const bf16_t* __restrict__ qb, const bf16_t* __restrict__ kb, const bf16_t* __restrict__ vt, bf16_t* __restrict__ ob, ...
;     ...
;         for (int kt = 0; kt < nkt; ++kt) {
;             asm volatile("s_waitcnt vmcnt(8)" ::: "memory");
;             asm volatile("s_waitcnt lgkmcnt(0)" ::: "memory"); __builtin_amdgcn_s_barrier();
;             ATT_ISSUE(kt + 3, (kt + 3) & 3);
;             const char* cur = lds + (kt & 3) * 32768;
;             const char* kl = cur + c * 8192; const char* vl = cur + 16384;
;             f32x16 sacc[2];
;             {
;                 bf16x8 kfr[2][4];
; #pragma unroll
;                 for (int kf = 0; kf < 2; ++kf)
; #pragma unroll
;                     for (int s = 0; s < 4; ++s) kfr[kf][s] = ldfrag(kl, kf * 32 + l31, 2 * s + hh);
; #pragma unroll
;                 for (int kf = 0; kf < 2; ++kf) {
;                     sacc[kf] = MFMA(kfr[kf][0], qf[0], negm);
; #pragma unroll
;                     for (int s = 1; s < 4; ++s) sacc[kf] = MFMA(kfr[kf][s], qf[s], sacc[kf]);
;                 }
;             }
;             bf16x8 vf[2][4];
; #pragma unroll
;             for (int ef = 0; ef < 4; ++ef) vf[0][ef] = ldfrag(vl, ef * 32 + l31, hh);
;             __builtin_amdgcn_sched_group_barrier(0x100, 4, 0);
; #pragma unroll
;             for (int g_ = 0; g_ < 4; ++g_) { __builtin_amdgcn_sched_group_barrier(0x008, 1, 0); __builtin_amdgcn_sched_group_barrier(0x100, 1, 0); }
;             __builtin_amdgcn_sched_group_barrier(0x008, 4, 0);
;             __builtin_amdgcn_sched_group_barrier(0x100, 4, 0);
;             float mx = fmaxf(fmaxf(sacc[0][0], sacc[0][1]), sacc[0][2]);
; #pragma unroll
;             for (int i = 3; i < 15; i += 2) mx = fmaxf(fmaxf(mx, sacc[0][i]), sacc[0][i + 1]);
;             mx = fmaxf(fmaxf(mx, sacc[0][15]), sacc[1][0]);
; #pragma unroll
;             for (int i = 1; i < 15; i += 2) mx = fmaxf(fmaxf(mx, sacc[1][i]), sacc[1][i + 1]);
;             mx = fmaxf(mx, sacc[1][15]);
;             if (kt == 0 || __any(mx > 8.0f)) {
;                 const float mfull = fmaxf(mx, __shfl_xor(mx, 32));
;                 const float delta = kt == 0 ? mfull : fmaxf(mfull, 0.f);
;                 const float alpha = kt == 0 ? 1.0f : __builtin_amdgcn_exp2f(-delta);
;                 l_run *= alpha;
; #pragma unroll
;                 for (int ef = 0; ef < 4; ++ef)
; #pragma unroll
.LBB0_215:
	s_waitcnt vmcnt(8)
	s_waitcnt lgkmcnt(0)
	s_barrier
	s_add_i32 s17, s19, 0xfffe8000
	s_and_b32 s17, s17, 0x18000
	s_add_i32 s17, s17, 0
	v_add3_u32 v65, s17, v192, v193
	v_add_u32_e32 v130, v65, v194
	ds_read_b128 v[82:85], v130
	v_add_u32_e32 v134, v65, v198
	ds_read_b128 v[86:89], v134
	v_add_u32_e32 v138, v65, v199
	v_add_u32_e32 v65, v65, v200
	ds_read_b128 v[90:93], v138
	ds_read_b128 v[94:97], v65
	s_waitcnt lgkmcnt(0)
	v_mfma_f32_32x32x16_bf16 v[98:113], v[82:85], v[114:117], v[66:81]
	ds_read_b128 v[130:133], v130 offset:4096
	s_mov_b32 s20, 0x41000000
	v_mfma_f32_32x32x16_bf16 v[98:113], v[86:89], v[118:121], v[98:113]
	ds_read_b128 v[134:137], v134 offset:4096
	v_mfma_f32_32x32x16_bf16 v[98:113], v[90:93], v[122:125], v[98:113]
	ds_read_b128 v[138:141], v138 offset:4096
	v_mfma_f32_32x32x16_bf16 v[98:113], v[94:97], v[126:129], v[98:113]
	ds_read_b128 v[142:145], v65 offset:4096
	v_add3_u32 v65, s17, v194, v193
	s_waitcnt lgkmcnt(0)
	v_mfma_f32_32x32x16_bf16 v[82:97], v[130:133], v[114:117], v[66:81]
	s_nop 7
	v_max_f32_e32 v146, v98, v98
	v_mfma_f32_32x32x16_bf16 v[82:97], v[134:137], v[118:121], v[82:97]
	v_mfma_f32_32x32x16_bf16 v[82:97], v[138:141], v[122:125], v[82:97]
	v_mfma_f32_32x32x16_bf16 v[82:97], v[142:145], v[126:129], v[82:97]
	ds_read_b128 v[142:145], v65 offset:16384
	ds_read_b128 v[138:141], v65 offset:20480
	ds_read_b128 v[134:137], v65 offset:24576
	ds_read_b128 v[130:133], v65 offset:28672
	v_max_f32_e32 v65, v99, v99
	v_max_f32_e32 v65, v146, v65
	v_max3_f32 v65, v65, v100, v101
	v_max3_f32 v65, v65, v102, v103
	v_max3_f32 v65, v65, v104, v105
	v_max3_f32 v65, v65, v106, v107
	v_max3_f32 v65, v65, v108, v109
	v_max3_f32 v65, v65, v110, v111
	v_max3_f32 v65, v65, v112, v113
	v_max3_f32 v65, v65, v82, v83
	v_max3_f32 v65, v65, v84, v85
	v_max3_f32 v65, v65, v86, v87
	v_max3_f32 v65, v65, v88, v89
	v_max3_f32 v65, v65, v90, v91
	v_max3_f32 v65, v65, v92, v93
	v_max3_f32 v65, v65, v94, v95
	v_max3_f32 v65, v65, v96, v97
	v_cmp_lt_f32_e32 vcc, s20, v65
	s_cbranch_vccz .LBB0_214
	ds_bpermute_b32 v146, v190, v65
	s_waitcnt lgkmcnt(0)
	v_max3_f32 v146, v65, v146, 0
	v_exp_f32_e64 v172, -v146
	v_pk_add_f32 v[98:99], v[98:99], v[146:147] op_sel_hi:[1,0] neg_lo:[0,1] neg_hi:[0,1]
	v_pk_add_f32 v[100:101], v[100:101], v[146:147] op_sel_hi:[1,0] neg_lo:[0,1] neg_hi:[0,1]
	v_pk_add_f32 v[102:103], v[102:103], v[146:147] op_sel_hi:[1,0] neg_lo:[0,1] neg_hi:[0,1]
	v_pk_mul_f32 v[14:15], v[14:15], v[172:173] op_sel_hi:[1,0]
	v_pk_mul_f32 v[12:13], v[12:13], v[172:173] op_sel_hi:[1,0]
	v_pk_mul_f32 v[10:11], v[10:11], v[172:173] op_sel_hi:[1,0]
	v_pk_mul_f32 v[8:9], v[8:9], v[172:173] op_sel_hi:[1,0]
	v_pk_mul_f32 v[6:7], v[6:7], v[172:173] op_sel_hi:[1,0]
	v_pk_mul_f32 v[4:5], v[4:5], v[172:173] op_sel_hi:[1,0]
	v_pk_mul_f32 v[2:3], v[2:3], v[172:173] op_sel_hi:[1,0]
	v_pk_mul_f32 v[0:1], v[0:1], v[172:173] op_sel_hi:[1,0]
	v_pk_mul_f32 v[30:31], v[30:31], v[172:173] op_sel_hi:[1,0]
	v_pk_mul_f32 v[28:29], v[28:29], v[172:173] op_sel_hi:[1,0]
	v_pk_mul_f32 v[26:27], v[26:27], v[172:173] op_sel_hi:[1,0]
	v_pk_mul_f32 v[24:25], v[24:25], v[172:173] op_sel_hi:[1,0]
	v_pk_mul_f32 v[22:23], v[22:23], v[172:173] op_sel_hi:[1,0]
	v_pk_mul_f32 v[20:21], v[20:21], v[172:173] op_sel_hi:[1,0]
	v_pk_mul_f32 v[18:19], v[18:19], v[172:173] op_sel_hi:[1,0]
	v_pk_mul_f32 v[16:17], v[16:17], v[172:173] op_sel_hi:[1,0]
	v_pk_mul_f32 v[46:47], v[46:47], v[172:173] op_sel_hi:[1,0]
	v_pk_mul_f32 v[44:45], v[44:45], v[172:173] op_sel_hi:[1,0]
	v_pk_mul_f32 v[42:43], v[42:43], v[172:173] op_sel_hi:[1,0]
	v_pk_mul_f32 v[40:41], v[40:41], v[172:173] op_sel_hi:[1,0]
	v_pk_mul_f32 v[38:39], v[38:39], v[172:173] op_sel_hi:[1,0]
	v_pk_mul_f32 v[36:37], v[36:37], v[172:173] op_sel_hi:[1,0]
	v_pk_mul_f32 v[34:35], v[34:35], v[172:173] op_sel_hi:[1,0]
	v_pk_mul_f32 v[32:33], v[32:33], v[172:173] op_sel_hi:[1,0]
	v_pk_mul_f32 v[62:63], v[62:63], v[172:173] op_sel_hi:[1,0]
	v_pk_mul_f32 v[60:61], v[60:61], v[172:173] op_sel_hi:[1,0]
	v_pk_mul_f32 v[58:59], v[58:59], v[172:173] op_sel_hi:[1,0]
	v_pk_mul_f32 v[56:57], v[56:57], v[172:173] op_sel_hi:[1,0]
	v_pk_mul_f32 v[54:55], v[54:55], v[172:173] op_sel_hi:[1,0]
	v_pk_mul_f32 v[52:53], v[52:53], v[172:173] op_sel_hi:[1,0]
	v_pk_mul_f32 v[50:51], v[50:51], v[172:173] op_sel_hi:[1,0]
	v_pk_mul_f32 v[48:49], v[48:49], v[172:173] op_sel_hi:[1,0]
	v_pk_add_f32 v[104:105], v[104:105], v[146:147] op_sel_hi:[1,0] neg_lo:[0,1] neg_hi:[0,1]
	v_pk_add_f32 v[106:107], v[106:107], v[146:147] op_sel_hi:[1,0] neg_lo:[0,1] neg_hi:[0,1]
	v_pk_add_f32 v[108:109], v[108:109], v[146:147] op_sel_hi:[1,0] neg_lo:[0,1] neg_hi:[0,1]
	v_pk_add_f32 v[110:111], v[110:111], v[146:147] op_sel_hi:[1,0] neg_lo:[0,1] neg_hi:[0,1]
	v_sub_f32_e32 v81, v81, v146
	v_sub_f32_e32 v80, v80, v146
	v_sub_f32_e32 v79, v79, v146
	v_sub_f32_e32 v78, v78, v146
	v_sub_f32_e32 v77, v77, v146
	v_sub_f32_e32 v76, v76, v146
	v_sub_f32_e32 v75, v75, v146
	v_sub_f32_e32 v74, v74, v146
	v_sub_f32_e32 v73, v73, v146
	v_sub_f32_e32 v72, v72, v146
	v_sub_f32_e32 v71, v71, v146
	v_sub_f32_e32 v70, v70, v146
	v_sub_f32_e32 v69, v69, v146
	v_sub_f32_e32 v68, v68, v146
	v_sub_f32_e32 v67, v67, v146
	v_sub_f32_e32 v66, v66, v146
	v_pk_add_f32 v[112:113], v[112:113], v[146:147] op_sel_hi:[1,0] neg_lo:[0,1] neg_hi:[0,1]
	v_sub_f32_e32 v82, v82, v146
	v_sub_f32_e32 v83, v83, v146
	v_sub_f32_e32 v84, v84, v146
	v_sub_f32_e32 v85, v85, v146
	v_sub_f32_e32 v86, v86, v146
	v_sub_f32_e32 v87, v87, v146
	v_sub_f32_e32 v88, v88, v146
	v_sub_f32_e32 v89, v89, v146
	v_sub_f32_e32 v90, v90, v146
	v_sub_f32_e32 v91, v91, v146
	v_sub_f32_e32 v92, v92, v146
	v_sub_f32_e32 v93, v93, v146
	v_sub_f32_e32 v94, v94, v146
	v_sub_f32_e32 v95, v95, v146
	v_sub_f32_e32 v96, v96, v146
	v_sub_f32_e32 v97, v97, v146
	v_mul_f32_e32 v64, v64, v172
	s_branch .LBB0_214

; #define MFMA16(a, b, c) __builtin_amdgcn_mfma_f32_16x16x32_bf16((a), (b), (c), 0, 0, 0)
; DI bf16x8 ldfrag(const char* lds, int row, int chunk) { return *(const bf16x8*)(lds + swz(row, chunk)); }
; #define LAS __attribute__((address_space(3)))
; template <bool RSTD, bool SWAP>
; DI void gemm_tile(gacc_t& acc, const bf16_t* __restrict__ A, int lda, const bf16_t* __restrict__ Bt, int ldb, int K,
;                   char* lds, int tid, int wr, int wc, int lane, const float* ssq_row) {
; #pragma unroll
;     for (int m = 0; m < 8; ++m)
; #pragma unroll
;         for (int n = 0; n < 4; ++n)
; #pragma unroll
;             for (int j = 0; j < 4; ++j) acc[m][n][j] = 0.f;
;     const int nk = K / 64;
;     const int fr = lane & 15, fq = lane >> 4;
;     const int srow = tid >> 3, sch = tid & 7;
;     const int cl = sch ^ ((srow >> 1) & 7);
;     const int wv = __builtin_amdgcn_readfirstlane(tid >> 6);
;     const bf16_t* ap = A + (long)srow * lda + cl * 8;
;     const bf16_t* bp = Bt + (long)srow * ldb + cl * 8;
;     LAS char* l3 = (LAS char*)lds;
;     ...
;     GEMM_ISSUE(0, 0);
;     ...
;     for (int kt = 0; kt < nk; ++kt) {
;         const char* cur = lds + (kt & 1) * 65536;
;         if (kt + 1 < nk) GEMM_ISSUE(kt + 1, (kt + 1) & 1);
;         bf16x8 bfr[2][4], afr[3];
; #pragma unroll
;         for (int n = 0; n < 4; ++n) bfr[0][n] = ldfrag(cur + 32768, wc * 64 + n * 16 + fr, fq);
;         afr[0] = ldfrag(cur, wr * 128 + fr, fq);
;         afr[1] = ldfrag(cur, wr * 128 + 16 + fr, fq);
; #pragma unroll
;         for (int idx = 0; idx < 16; ++idx) {
;             const int ks = idx >> 3, m = idx & 7;
;             if (idx < 14) afr[(idx + 2) % 3] = ldfrag(cur, wr * 128 + ((idx + 2) & 7) * 16 + fr, ((idx + 2) >> 3) * 4 + fq);
;             if (ks == 0 && m >= 2 && m < 6) bfr[1][m - 2] = ldfrag(cur + 32768, wc * 64 + (m - 2) * 16 + fr, 4 + fq);
; #pragma unroll
;             for (int n = 0; n < 4; ++n) acc[m][n] = SWAP ? MFMA16(bfr[ks][n], afr[idx % 3], acc[m][n]) : MFMA16(afr[idx % 3], bfr[ks][n], acc[m][n]);
.LBB0_617:
	s_or_b64 exec, exec, s[48:49]
	s_waitcnt vmcnt(0)
	v_mov_b32_e32 v0, 0
	v_lshl_add_u64 v[138:139], v[134:135], 0, s[46:47]
	v_lshl_add_u64 v[140:141], v[136:137], 0, s[44:45]
	s_mov_b64 s[12:13], 0
	s_mov_b32 s44, 0x10000
	v_mov_b32_e32 v1, v0
	v_mov_b32_e32 v2, v0
	v_mov_b32_e32 v3, v0
	v_mov_b32_e32 v4, v0
	v_mov_b32_e32 v5, v0
	v_mov_b32_e32 v6, v0
	v_mov_b32_e32 v7, v0
	v_mov_b32_e32 v8, v0
	v_mov_b32_e32 v9, v0
	v_mov_b32_e32 v10, v0
	v_mov_b32_e32 v11, v0
	v_mov_b32_e32 v12, v0
	v_mov_b32_e32 v13, v0
	v_mov_b32_e32 v14, v0
	v_mov_b32_e32 v15, v0
	v_mov_b32_e32 v16, v0
	v_mov_b32_e32 v17, v0
	v_mov_b32_e32 v18, v0
	v_mov_b32_e32 v19, v0
	v_mov_b32_e32 v20, v0
	v_mov_b32_e32 v21, v0
	v_mov_b32_e32 v22, v0
	v_mov_b32_e32 v23, v0
	v_mov_b32_e32 v24, v0
	v_mov_b32_e32 v25, v0
	v_mov_b32_e32 v26, v0
	v_mov_b32_e32 v27, v0
	v_mov_b32_e32 v28, v0
	v_mov_b32_e32 v29, v0
	v_mov_b32_e32 v30, v0
	v_mov_b32_e32 v31, v0
	v_mov_b32_e32 v32, v0
	v_mov_b32_e32 v33, v0
	v_mov_b32_e32 v34, v0
	v_mov_b32_e32 v35, v0
	v_mov_b32_e32 v36, v0
	v_mov_b32_e32 v37, v0
	v_mov_b32_e32 v38, v0
	v_mov_b32_e32 v39, v0
	v_mov_b32_e32 v40, v0
	v_mov_b32_e32 v41, v0
	v_mov_b32_e32 v42, v0
	v_mov_b32_e32 v43, v0
	v_mov_b32_e32 v44, v0
	v_mov_b32_e32 v45, v0
	v_mov_b32_e32 v46, v0
	v_mov_b32_e32 v47, v0
	v_mov_b32_e32 v48, v0
	v_mov_b32_e32 v49, v0
	v_mov_b32_e32 v50, v0
	v_mov_b32_e32 v51, v0
	v_mov_b32_e32 v52, v0
	v_mov_b32_e32 v53, v0
	v_mov_b32_e32 v54, v0
	v_mov_b32_e32 v55, v0
	v_mov_b32_e32 v56, v0
	v_mov_b32_e32 v57, v0
	v_mov_b32_e32 v58, v0
	v_mov_b32_e32 v59, v0
	v_mov_b32_e32 v60, v0
	v_mov_b32_e32 v61, v0
	v_mov_b32_e32 v62, v0
	v_mov_b32_e32 v63, v0
	v_mov_b32_e32 v64, v0
	v_mov_b32_e32 v65, v0
	v_mov_b32_e32 v66, v0
	v_mov_b32_e32 v67, v0
	v_mov_b32_e32 v68, v0
	v_mov_b32_e32 v69, v0
	v_mov_b32_e32 v70, v0
	v_mov_b32_e32 v71, v0
	v_mov_b32_e32 v72, v0
	v_mov_b32_e32 v73, v0
	v_mov_b32_e32 v74, v0
	v_mov_b32_e32 v75, v0
	v_mov_b32_e32 v76, v0
	v_mov_b32_e32 v77, v0
	v_mov_b32_e32 v78, v0
	v_mov_b32_e32 v79, v0
	v_mov_b32_e32 v80, v0
	v_mov_b32_e32 v81, v0
	v_mov_b32_e32 v82, v0
	v_mov_b32_e32 v83, v0
	v_mov_b32_e32 v84, v0
	v_mov_b32_e32 v85, v0
	v_mov_b32_e32 v86, v0
	v_mov_b32_e32 v87, v0
	v_mov_b32_e32 v88, v0
	v_mov_b32_e32 v89, v0
	v_mov_b32_e32 v90, v0
	v_mov_b32_e32 v91, v0
	v_mov_b32_e32 v92, v0
	v_mov_b32_e32 v93, v0
	v_mov_b32_e32 v94, v0
	v_mov_b32_e32 v95, v0
	v_mov_b32_e32 v96, v0
	v_mov_b32_e32 v97, v0
	v_mov_b32_e32 v98, v0
	v_mov_b32_e32 v99, v0
	v_mov_b32_e32 v100, v0
	v_mov_b32_e32 v101, v0
	v_mov_b32_e32 v102, v0
	v_mov_b32_e32 v103, v0
	v_mov_b32_e32 v104, v0
	v_mov_b32_e32 v105, v0
	v_mov_b32_e32 v106, v0
	v_mov_b32_e32 v107, v0
	v_mov_b32_e32 v108, v0
	v_mov_b32_e32 v109, v0
	v_mov_b32_e32 v110, v0
	v_mov_b32_e32 v111, v0
	v_mov_b32_e32 v112, v0
	v_mov_b32_e32 v113, v0
	v_mov_b32_e32 v114, v0
	v_mov_b32_e32 v115, v0
	v_mov_b32_e32 v116, v0
	v_mov_b32_e32 v117, v0
	v_mov_b32_e32 v118, v0
	v_mov_b32_e32 v119, v0
	v_mov_b32_e32 v120, v0
	v_mov_b32_e32 v121, v0
	v_mov_b32_e32 v122, v0
	v_mov_b32_e32 v123, v0
	v_mov_b32_e32 v124, v0
	v_mov_b32_e32 v125, v0
	v_mov_b32_e32 v126, v0
	v_mov_b32_e32 v127, v0
	v_mov_b32_e32 v198, 0
	v_mov_b32_e32 v199, 0
	v_mov_b32_e32 v200, 0
	v_mov_b32_e32 v201, 0
	v_mov_b32_e32 v202, 0
	v_mov_b32_e32 v203, 0
	v_mov_b32_e32 v204, 0
	v_mov_b32_e32 v205, 0
	v_mov_b32_e32 v206, 0
	v_mov_b32_e32 v207, 0
	v_mov_b32_e32 v208, 0
	v_mov_b32_e32 v209, 0
	v_mov_b32_e32 v210, 0
	v_mov_b32_e32 v211, 0
	v_mov_b32_e32 v212, 0
	v_mov_b32_e32 v213, 0
	v_mov_b32_e32 v214, 0
	v_mov_b32_e32 v215, 0
	v_mov_b32_e32 v216, 0
	v_mov_b32_e32 v217, 0
	v_mov_b32_e32 v218, 0
	v_mov_b32_e32 v219, 0
	v_mov_b32_e32 v220, 0
	v_mov_b32_e32 v221, 0
	v_mov_b32_e32 v222, 0
	v_mov_b32_e32 v223, 0
	v_mov_b32_e32 v224, 0
	v_mov_b32_e32 v225, 0
	v_mov_b32_e32 v236, 0
	v_mov_b32_e32 v237, 0
	v_mov_b32_e32 v238, 0
	v_mov_b32_e32 v239, 0
	s_waitcnt vmcnt(0) lgkmcnt(0)
	s_barrier
.LBB0_618:
	s_add_i32 s45, s44, 0xffff0000
	s_and_b32 s45, s45, 0x10000
	s_add_i32 s45, s45, 0
	v_add_u32_e32 v146, s45, v144
	v_add3_u32 v161, v146, v150, v151
	v_add_u32_e32 v166, v146, v148
	ds_read_b128 v[162:165], v161 offset:32768
	ds_read_b128 v[172:175], v161 offset:34816
	ds_read_b128 v[180:183], v161 offset:36864
	ds_read_b128 v[186:189], v161 offset:38912
	ds_read_b128 v[176:179], v166
	ds_read_b128 v[190:193], v166 offset:2048
	v_add_u32_e32 v161, v146, v152
	ds_read_b128 v[194:197], v166 offset:4096
	v_lshl_add_u64 v[240:241], v[140:141], 0, s[12:13]
	v_lshl_add_u64 v[242:243], v[138:139], 0, s[12:13]
	s_and_b32 s48, s44, 0x10000
	s_add_i32 s48, s43, s48
	s_mov_b64 s[46:47], 0x2ee40080
	v_lshl_add_u64 v[232:233], v[240:241], 0, s[46:47]
	s_mov_b32 m0, s48
	v_mfma_f32_16x16x32_bf16 v[60:63], v[198:201], v[214:217], v[60:63]
	global_load_lds_dwordx4 v[232:233], off
	v_mfma_f32_16x16x32_bf16 v[56:59], v[202:205], v[214:217], v[56:59]
	s_mov_b64 s[46:47], 0x1c80080
	v_lshl_add_u64 v[234:235], v[242:243], 0, s[46:47]
	s_add_i32 m0, s48, 0x8000
	v_mfma_f32_16x16x32_bf16 v[52:55], v[206:209], v[214:217], v[52:55]
	global_load_lds_dwordx4 v[234:235], off
	v_mfma_f32_16x16x32_bf16 v[48:51], v[210:213], v[214:217], v[48:51]
	s_mov_b64 s[46:47], 0x2ee60080
	v_lshl_add_u64 v[232:233], v[240:241], 0, s[46:47]
	s_add_i32 m0, s48, 0x2000
	v_mfma_f32_16x16x32_bf16 v[44:47], v[198:201], v[218:221], v[44:47]
	global_load_lds_dwordx4 v[232:233], off
	v_mfma_f32_16x16x32_bf16 v[40:43], v[202:205], v[218:221], v[40:43]
	s_mov_b64 s[46:47], 0x1ca0080
	v_lshl_add_u64 v[234:235], v[242:243], 0, s[46:47]
	s_add_i32 m0, s48, 0xa000
	v_mfma_f32_16x16x32_bf16 v[36:39], v[206:209], v[218:221], v[36:39]
	global_load_lds_dwordx4 v[234:235], off
	v_mfma_f32_16x16x32_bf16 v[32:35], v[210:213], v[218:221], v[32:35]
	s_mov_b64 s[46:47], 0x2ee80080
	v_lshl_add_u64 v[232:233], v[240:241], 0, s[46:47]
	s_add_i32 m0, s48, 0x4000
	v_mfma_f32_16x16x32_bf16 v[28:31], v[198:201], v[222:225], v[28:31]
	global_load_lds_dwordx4 v[232:233], off
	v_mfma_f32_16x16x32_bf16 v[24:27], v[202:205], v[222:225], v[24:27]
	s_mov_b64 s[46:47], 0x1cc0080
	v_lshl_add_u64 v[234:235], v[242:243], 0, s[46:47]
	s_add_i32 m0, s48, 0xc000
	v_mfma_f32_16x16x32_bf16 v[20:23], v[206:209], v[222:225], v[20:23]
	global_load_lds_dwordx4 v[234:235], off
	v_mfma_f32_16x16x32_bf16 v[16:19], v[210:213], v[222:225], v[16:19]
	s_mov_b64 s[46:47], 0x2eea0080
	v_lshl_add_u64 v[232:233], v[240:241], 0, s[46:47]
	s_add_i32 m0, s48, 0x6000
	v_mfma_f32_16x16x32_bf16 v[12:15], v[198:201], v[236:239], v[12:15]
	global_load_lds_dwordx4 v[232:233], off
	v_mfma_f32_16x16x32_bf16 v[8:11], v[202:205], v[236:239], v[8:11]
	s_mov_b64 s[46:47], 0x1ce0080
	v_lshl_add_u64 v[234:235], v[242:243], 0, s[46:47]
	s_add_i32 m0, s48, 0xe000
	v_mfma_f32_16x16x32_bf16 v[4:7], v[206:209], v[236:239], v[4:7]
	global_load_lds_dwordx4 v[234:235], off
	v_mfma_f32_16x16x32_bf16 v[0:3], v[210:213], v[236:239], v[0:3]
	s_waitcnt lgkmcnt(0)
; #define MFMA16(a, b, c) __builtin_amdgcn_mfma_f32_16x16x32_bf16((a), (b), (c), 0, 0, 0)
; DI bf16x8 ldfrag(const char* lds, int row, int chunk) { return *(const bf16x8*)(lds + swz(row, chunk)); }
; #define GEMM_SG1() do { __builtin_amdgcn_sched_group_barrier(0x100, 1, 0); __builtin_amdgcn_sched_group_barrier(0x008, 4, 0); } while (0)
; #define GEMM_SG2() do { __builtin_amdgcn_sched_group_barrier(0x100, 2, 0); __builtin_amdgcn_sched_group_barrier(0x008, 4, 0); } while (0)
; template <bool RSTD, bool SWAP>
; DI void gemm_tile(gacc_t& acc, const bf16_t* __restrict__ A, int lda, const bf16_t* __restrict__ Bt, int ldb, int K,
;                   char* lds, int tid, int wr, int wc, int lane, const float* ssq_row) {
;     ...
;         for (int idx = 0; idx < 16; ++idx) {
;             const int ks = idx >> 3, m = idx & 7;
;             if (idx < 14) afr[(idx + 2) % 3] = ldfrag(cur, wr * 128 + ((idx + 2) & 7) * 16 + fr, ((idx + 2) >> 3) * 4 + fq);
;             if (ks == 0 && m >= 2 && m < 6) bfr[1][m - 2] = ldfrag(cur + 32768, wc * 64 + (m - 2) * 16 + fr, 4 + fq);
; #pragma unroll
;             for (int n = 0; n < 4; ++n) acc[m][n] = SWAP ? MFMA16(bfr[ks][n], afr[idx % 3], acc[m][n]) : MFMA16(afr[idx % 3], bfr[ks][n], acc[m][n]);
;         }
;         __builtin_amdgcn_sched_group_barrier(0x100, 6, 0);
;     ...
;         GEMM_SG1(); GEMM_SG1(); GEMM_SG2(); GEMM_SG2(); GEMM_SG2(); GEMM_SG2(); GEMM_SG1(); GEMM_SG1();
;         GEMM_SG1(); GEMM_SG1(); GEMM_SG1(); GEMM_SG1(); GEMM_SG1(); GEMM_SG1();
;         __builtin_amdgcn_sched_group_barrier(0x008, 8, 0);
;         __builtin_amdgcn_sched_barrier(0);
;         asm volatile("s_waitcnt vmcnt(0)" ::: "memory");
;         __syncthreads();
	v_mfma_f32_16x16x32_bf16 v[124:127], v[162:165], v[176:179], v[124:127]
	v_add_u32_e32 v146, v146, v154
	v_mfma_f32_16x16x32_bf16 v[120:123], v[172:175], v[176:179], v[120:123]
	v_mfma_f32_16x16x32_bf16 v[116:119], v[180:183], v[176:179], v[116:119]
	v_mfma_f32_16x16x32_bf16 v[112:115], v[186:189], v[176:179], v[112:115]
	ds_read_b128 v[176:179], v161
	v_add_u32_e32 v161, s45, v149
	v_add_u32_e32 v167, v161, v153
	v_mfma_f32_16x16x32_bf16 v[108:111], v[162:165], v[190:193], v[108:111]
	v_mfma_f32_16x16x32_bf16 v[104:107], v[172:175], v[190:193], v[104:107]
	v_mfma_f32_16x16x32_bf16 v[100:103], v[180:183], v[190:193], v[100:103]
	v_mfma_f32_16x16x32_bf16 v[96:99], v[186:189], v[190:193], v[96:99]
	ds_read_b128 v[190:193], v166 offset:8192
	ds_read_b128 v[198:201], v167 offset:32768
	v_mfma_f32_16x16x32_bf16 v[92:95], v[162:165], v[194:197], v[92:95]
	v_mfma_f32_16x16x32_bf16 v[88:91], v[172:175], v[194:197], v[88:91]
	v_mfma_f32_16x16x32_bf16 v[84:87], v[180:183], v[194:197], v[84:87]
	v_mfma_f32_16x16x32_bf16 v[80:83], v[186:189], v[194:197], v[80:83]
	ds_read_b128 v[194:197], v166 offset:10240
	ds_read_b128 v[202:205], v167 offset:34816
	s_waitcnt lgkmcnt(0)
	v_mfma_f32_16x16x32_bf16 v[76:79], v[162:165], v[176:179], v[76:79]
	v_mfma_f32_16x16x32_bf16 v[72:75], v[172:175], v[176:179], v[72:75]
	v_mfma_f32_16x16x32_bf16 v[68:71], v[180:183], v[176:179], v[68:71]
	v_mfma_f32_16x16x32_bf16 v[64:67], v[186:189], v[176:179], v[64:67]
	ds_read_b128 v[176:179], v166 offset:12288
	v_add_u32_e32 v166, v161, v155
	ds_read_b128 v[206:209], v167 offset:36864
	v_mfma_f32_16x16x32_bf16 v[60:63], v[162:165], v[190:193], v[60:63]
	v_mfma_f32_16x16x32_bf16 v[56:59], v[172:175], v[190:193], v[56:59]
	v_mfma_f32_16x16x32_bf16 v[52:55], v[180:183], v[190:193], v[52:55]
	v_mfma_f32_16x16x32_bf16 v[48:51], v[186:189], v[190:193], v[48:51]
	ds_read_b128 v[210:213], v166 offset:38912
	ds_read_b128 v[190:193], v146
	v_add_u32_e32 v146, v161, v148
	v_mfma_f32_16x16x32_bf16 v[44:47], v[162:165], v[194:197], v[44:47]
	v_add_u32_e32 v166, v161, v152
	v_mfma_f32_16x16x32_bf16 v[40:43], v[172:175], v[194:197], v[40:43]
	v_mfma_f32_16x16x32_bf16 v[36:39], v[180:183], v[194:197], v[36:39]
	v_mfma_f32_16x16x32_bf16 v[32:35], v[186:189], v[194:197], v[32:35]
	ds_read_b128 v[194:197], v146
	v_add_u32_e32 v230, v161, v154
	s_waitcnt lgkmcnt(0)
	v_mfma_f32_16x16x32_bf16 v[28:31], v[162:165], v[176:179], v[28:31]
	v_mfma_f32_16x16x32_bf16 v[24:27], v[172:175], v[176:179], v[24:27]
	v_mfma_f32_16x16x32_bf16 v[20:23], v[180:183], v[176:179], v[20:23]
	v_mfma_f32_16x16x32_bf16 v[16:19], v[186:189], v[176:179], v[16:19]
	ds_read_b128 v[176:179], v146 offset:2048
	v_mfma_f32_16x16x32_bf16 v[12:15], v[162:165], v[190:193], v[12:15]
	v_mfma_f32_16x16x32_bf16 v[8:11], v[172:175], v[190:193], v[8:11]
	v_mfma_f32_16x16x32_bf16 v[4:7], v[180:183], v[190:193], v[4:7]
	v_mfma_f32_16x16x32_bf16 v[0:3], v[186:189], v[190:193], v[0:3]
	ds_read_b128 v[162:165], v146 offset:4096
	v_mfma_f32_16x16x32_bf16 v[124:127], v[198:201], v[194:197], v[124:127]
	v_mfma_f32_16x16x32_bf16 v[120:123], v[202:205], v[194:197], v[120:123]
	v_mfma_f32_16x16x32_bf16 v[116:119], v[206:209], v[194:197], v[116:119]
	v_mfma_f32_16x16x32_bf16 v[112:115], v[210:213], v[194:197], v[112:115]
	ds_read_b128 v[172:175], v166
	ds_read_b128 v[214:217], v146 offset:8192
	s_waitcnt lgkmcnt(0)
	v_mfma_f32_16x16x32_bf16 v[108:111], v[198:201], v[176:179], v[108:111]
	v_mfma_f32_16x16x32_bf16 v[104:107], v[202:205], v[176:179], v[104:107]
	v_mfma_f32_16x16x32_bf16 v[100:103], v[206:209], v[176:179], v[100:103]
	v_mfma_f32_16x16x32_bf16 v[96:99], v[210:213], v[176:179], v[96:99]
	ds_read_b128 v[218:221], v146 offset:10240
	v_mfma_f32_16x16x32_bf16 v[92:95], v[198:201], v[162:165], v[92:95]
	v_mfma_f32_16x16x32_bf16 v[88:91], v[202:205], v[162:165], v[88:91]
	v_mfma_f32_16x16x32_bf16 v[84:87], v[206:209], v[162:165], v[84:87]
	v_mfma_f32_16x16x32_bf16 v[80:83], v[210:213], v[162:165], v[80:83]
	ds_read_b128 v[222:225], v146 offset:12288
	ds_read_b128 v[236:239], v230
	v_mfma_f32_16x16x32_bf16 v[76:79], v[198:201], v[172:175], v[76:79]
	v_mfma_f32_16x16x32_bf16 v[72:75], v[202:205], v[172:175], v[72:75]
	v_mfma_f32_16x16x32_bf16 v[68:71], v[206:209], v[172:175], v[68:71]
	v_mfma_f32_16x16x32_bf16 v[64:67], v[210:213], v[172:175], v[64:67]
	s_waitcnt lgkmcnt(0)
	s_waitcnt vmcnt(0)
	s_add_u32 s12, s12, 0x80
	s_addc_u32 s13, s13, 0
	s_add_i32 s44, s44, 0x10000
	s_cmpk_lg_i32 s12, 0x780
	s_waitcnt vmcnt(0)
	s_barrier
	s_cbranch_scc1 .LBB0_618
; #define MFMA16(a, b, c) __builtin_amdgcn_mfma_f32_16x16x32_bf16((a), (b), (c), 0, 0, 0)
; DI bf16x8 ldfrag(const char* lds, int row, int chunk) { return *(const bf16x8*)(lds + swz(row, chunk)); }
; template <bool RSTD, bool SWAP>
; DI void gemm_tile(gacc_t& acc, const bf16_t* __restrict__ A, int lda, const bf16_t* __restrict__ Bt, int ldb, int K,
;                   char* lds, int tid, int wr, int wc, int lane, const float* ssq_row) {
;     ...
;         for (int idx = 0; idx < 16; ++idx) {
;             const int ks = idx >> 3, m = idx & 7;
;             if (idx < 14) afr[(idx + 2) % 3] = ldfrag(cur, wr * 128 + ((idx + 2) & 7) * 16 + fr, ((idx + 2) >> 3) * 4 + fq);
;             if (ks == 0 && m >= 2 && m < 6) bfr[1][m - 2] = ldfrag(cur + 32768, wc * 64 + (m - 2) * 16 + fr, 4 + fq);
; #pragma unroll
;             for (int n = 0; n < 4; ++n) acc[m][n] = SWAP ? MFMA16(bfr[ks][n], afr[idx % 3], acc[m][n]) : MFMA16(afr[idx % 3], bfr[ks][n], acc[m][n]);
;         }
	v_mfma_f32_16x16x32_bf16 v[60:63], v[198:201], v[214:217], v[60:63]
	v_mfma_f32_16x16x32_bf16 v[56:59], v[202:205], v[214:217], v[56:59]
	v_mfma_f32_16x16x32_bf16 v[52:55], v[206:209], v[214:217], v[52:55]
	v_mfma_f32_16x16x32_bf16 v[48:51], v[210:213], v[214:217], v[48:51]
	v_mfma_f32_16x16x32_bf16 v[44:47], v[198:201], v[218:221], v[44:47]
	v_mfma_f32_16x16x32_bf16 v[40:43], v[202:205], v[218:221], v[40:43]
	v_mfma_f32_16x16x32_bf16 v[36:39], v[206:209], v[218:221], v[36:39]
	v_mfma_f32_16x16x32_bf16 v[32:35], v[210:213], v[218:221], v[32:35]
	v_mfma_f32_16x16x32_bf16 v[28:31], v[198:201], v[222:225], v[28:31]
	v_mfma_f32_16x16x32_bf16 v[24:27], v[202:205], v[222:225], v[24:27]
	v_mfma_f32_16x16x32_bf16 v[20:23], v[206:209], v[222:225], v[20:23]
	v_mfma_f32_16x16x32_bf16 v[16:19], v[210:213], v[222:225], v[16:19]
	v_mfma_f32_16x16x32_bf16 v[12:15], v[198:201], v[236:239], v[12:15]
	v_mfma_f32_16x16x32_bf16 v[8:11], v[202:205], v[236:239], v[8:11]
	v_mfma_f32_16x16x32_bf16 v[4:7], v[206:209], v[236:239], v[4:7]
	v_mfma_f32_16x16x32_bf16 v[0:3], v[210:213], v[236:239], v[0:3]
	ds_read_b128 v[138:141], v160
	ds_read_b128 v[162:165], v160 offset:2048
	ds_read_b128 v[176:179], v160 offset:4096
	ds_read_b128 v[180:183], v160 offset:6144
	v_add_u32_e32 v146, v156, v148
	ds_read_b128 v[172:175], v146
	ds_read_b128 v[186:189], v146 offset:2048
	v_add_u32_e32 v161, v156, v152
	ds_read_b128 v[190:193], v146 offset:4096
	s_waitcnt lgkmcnt(2)
	v_mfma_f32_16x16x32_bf16 v[124:127], v[138:141], v[172:175], v[124:127]
	v_mfma_f32_16x16x32_bf16 v[120:123], v[162:165], v[172:175], v[120:123]
	v_mfma_f32_16x16x32_bf16 v[116:119], v[176:179], v[172:175], v[116:119]
	v_mfma_f32_16x16x32_bf16 v[112:115], v[180:183], v[172:175], v[112:115]
	ds_read_b128 v[172:175], v161
	v_add_u32_e32 v161, v157, v153
	s_waitcnt lgkmcnt(2)
	v_mfma_f32_16x16x32_bf16 v[108:111], v[138:141], v[186:189], v[108:111]
	v_mfma_f32_16x16x32_bf16 v[104:107], v[162:165], v[186:189], v[104:107]
	v_mfma_f32_16x16x32_bf16 v[100:103], v[176:179], v[186:189], v[100:103]
	v_mfma_f32_16x16x32_bf16 v[96:99], v[180:183], v[186:189], v[96:99]
	ds_read_b128 v[186:189], v146 offset:8192
	ds_read_b128 v[194:197], v161
	s_waitcnt lgkmcnt(3)
	v_mfma_f32_16x16x32_bf16 v[92:95], v[138:141], v[190:193], v[92:95]
	v_mfma_f32_16x16x32_bf16 v[88:91], v[162:165], v[190:193], v[88:91]
	v_mfma_f32_16x16x32_bf16 v[84:87], v[176:179], v[190:193], v[84:87]
	v_mfma_f32_16x16x32_bf16 v[80:83], v[180:183], v[190:193], v[80:83]
	ds_read_b128 v[190:193], v146 offset:10240
	ds_read_b128 v[198:201], v161 offset:2048
	s_waitcnt lgkmcnt(4)
	v_mfma_f32_16x16x32_bf16 v[76:79], v[138:141], v[172:175], v[76:79]
	v_mfma_f32_16x16x32_bf16 v[72:75], v[162:165], v[172:175], v[72:75]
	v_mfma_f32_16x16x32_bf16 v[68:71], v[176:179], v[172:175], v[68:71]
	v_mfma_f32_16x16x32_bf16 v[64:67], v[180:183], v[172:175], v[64:67]
	ds_read_b128 v[172:175], v146 offset:12288
	v_add_u32_e32 v146, v156, v154
	ds_read_b128 v[202:205], v161 offset:4096
	s_waitcnt lgkmcnt(5)
	v_mfma_f32_16x16x32_bf16 v[60:63], v[138:141], v[186:189], v[60:63]
	v_mfma_f32_16x16x32_bf16 v[56:59], v[162:165], v[186:189], v[56:59]
	v_mfma_f32_16x16x32_bf16 v[52:55], v[176:179], v[186:189], v[52:55]
	v_mfma_f32_16x16x32_bf16 v[48:51], v[180:183], v[186:189], v[48:51]
	ds_read_b128 v[186:189], v146
	v_add_u32_e32 v146, v157, v155
	ds_read_b128 v[206:209], v146 offset:6144
	v_add_u32_e32 v146, v158, v148
	s_waitcnt lgkmcnt(5)
	v_mfma_f32_16x16x32_bf16 v[44:47], v[138:141], v[190:193], v[44:47]
	v_mfma_f32_16x16x32_bf16 v[40:43], v[162:165], v[190:193], v[40:43]
	v_mfma_f32_16x16x32_bf16 v[36:39], v[176:179], v[190:193], v[36:39]
	v_mfma_f32_16x16x32_bf16 v[32:35], v[180:183], v[190:193], v[32:35]
	ds_read_b128 v[190:193], v146
	s_waitcnt lgkmcnt(4)
	v_mfma_f32_16x16x32_bf16 v[28:31], v[138:141], v[172:175], v[28:31]
	v_mfma_f32_16x16x32_bf16 v[24:27], v[162:165], v[172:175], v[24:27]
	v_mfma_f32_16x16x32_bf16 v[20:23], v[176:179], v[172:175], v[20:23]
	v_mfma_f32_16x16x32_bf16 v[16:19], v[180:183], v[172:175], v[16:19]
	ds_read_b128 v[172:175], v146 offset:2048
	s_waitcnt lgkmcnt(3)
; #define MFMA16(a, b, c) __builtin_amdgcn_mfma_f32_16x16x32_bf16((a), (b), (c), 0, 0, 0)
; DI bf16x8 ldfrag(const char* lds, int row, int chunk) { return *(const bf16x8*)(lds + swz(row, chunk)); }
; template <bool RSTD, bool SWAP>
; DI void gemm_tile(gacc_t& acc, const bf16_t* __restrict__ A, int lda, const bf16_t* __restrict__ Bt, int ldb, int K,
;                   char* lds, int tid, int wr, int wc, int lane, const float* ssq_row) {
;     ...
;         for (int idx = 0; idx < 16; ++idx) {
;             const int ks = idx >> 3, m = idx & 7;
;             if (idx < 14) afr[(idx + 2) % 3] = ldfrag(cur, wr * 128 + ((idx + 2) & 7) * 16 + fr, ((idx + 2) >> 3) * 4 + fq);
;             if (ks == 0 && m >= 2 && m < 6) bfr[1][m - 2] = ldfrag(cur + 32768, wc * 64 + (m - 2) * 16 + fr, 4 + fq);
; #pragma unroll
;             for (int n = 0; n < 4; ++n) acc[m][n] = SWAP ? MFMA16(bfr[ks][n], afr[idx % 3], acc[m][n]) : MFMA16(afr[idx % 3], bfr[ks][n], acc[m][n]);
;         }
;         __builtin_amdgcn_sched_group_barrier(0x100, 6, 0);
;     ...
;         GEMM_SG1(); GEMM_SG1(); GEMM_SG2(); GEMM_SG2(); GEMM_SG2(); GEMM_SG2(); GEMM_SG1(); GEMM_SG1();
;         GEMM_SG1(); GEMM_SG1(); GEMM_SG1(); GEMM_SG1(); GEMM_SG1(); GEMM_SG1();
;         __builtin_amdgcn_sched_group_barrier(0x008, 8, 0);
;         __builtin_amdgcn_sched_barrier(0);
;         asm volatile("s_waitcnt vmcnt(0)" ::: "memory");
;         __syncthreads();
;     DI void operator()(gacc_t& acc, int pm, int pn, char* lds, int tid, int wr, int wc, int lane) const {
;     ...
;         constexpr int RS = 528;
;         const float* rl = (const float*)(lds + RSTD_OFF) + wr * 128 + fr;
;         {
;             char* lbase = lds + (wr * 128 + fr) * RS + (wc * 64 + 4 * fq) * 2;
;             bf16_t* hrow = halo + (long)(pm * 4) * 5632 + pn * 256 + wc * 64 + 4 * fq;
; #pragma unroll
;             for (int m = 0; m < 8; ++m) {
;                 const float r = rl[m * 16];
; #pragma unroll
;                 for (int n = 0; n < 4; ++n) {
;                     u32x2 w; w.x = pk2(acc[m][n][0] * r, acc[m][n][1] * r); w.y = pk2(acc[m][n][2] * r, acc[m][n][3] * r);
;                     *(u32x2*)(lbase + m * 16 * RS + n * 32) = w;
;                     if (m == 0 && wr == 0 && fr < 2) *(u32x2*)(hrow + fr * 5632 + n * 16) = w;
;                     if (m == 7 && wr == 1 && fr >= 14) *(u32x2*)(hrow + (fr - 12) * 5632 + n * 16) = w;
	v_mfma_f32_16x16x32_bf16 v[12:15], v[138:141], v[186:189], v[12:15]
	v_mfma_f32_16x16x32_bf16 v[8:11], v[162:165], v[186:189], v[8:11]
	v_mfma_f32_16x16x32_bf16 v[4:7], v[176:179], v[186:189], v[4:7]
	v_mfma_f32_16x16x32_bf16 v[138:141], v[180:183], v[186:189], v[0:3]
	s_nop 2
	ds_read_b128 v[0:3], v146 offset:4096
	s_waitcnt lgkmcnt(2)
	v_mfma_f32_16x16x32_bf16 v[164:167], v[194:197], v[190:193], v[124:127]
	v_mfma_f32_16x16x32_bf16 v[120:123], v[198:201], v[190:193], v[120:123]
	s_nop 1
	v_add_u32_e32 v124, v158, v152
	v_mfma_f32_16x16x32_bf16 v[116:119], v[202:205], v[190:193], v[116:119]
	v_mfma_f32_16x16x32_bf16 v[112:115], v[206:209], v[190:193], v[112:115]
	ds_read_b128 v[124:127], v124
	s_waitcnt lgkmcnt(2)
	v_mfma_f32_16x16x32_bf16 v[108:111], v[194:197], v[172:175], v[108:111]
	v_mfma_f32_16x16x32_bf16 v[104:107], v[198:201], v[172:175], v[104:107]
	v_mfma_f32_16x16x32_bf16 v[100:103], v[202:205], v[172:175], v[100:103]
	v_mfma_f32_16x16x32_bf16 v[96:99], v[206:209], v[172:175], v[96:99]
	ds_read_b128 v[172:175], v146 offset:8192
	s_waitcnt lgkmcnt(2)
	v_mfma_f32_16x16x32_bf16 v[92:95], v[194:197], v[0:3], v[92:95]
	v_mfma_f32_16x16x32_bf16 v[88:91], v[198:201], v[0:3], v[88:91]
	v_mfma_f32_16x16x32_bf16 v[84:87], v[202:205], v[0:3], v[84:87]
	v_mfma_f32_16x16x32_bf16 v[80:83], v[206:209], v[0:3], v[80:83]
	ds_read_b128 v[0:3], v146 offset:10240
	s_waitcnt lgkmcnt(2)
	v_mfma_f32_16x16x32_bf16 v[76:79], v[194:197], v[124:127], v[76:79]
	v_mfma_f32_16x16x32_bf16 v[72:75], v[198:201], v[124:127], v[72:75]
	v_mfma_f32_16x16x32_bf16 v[68:71], v[202:205], v[124:127], v[68:71]
	v_mfma_f32_16x16x32_bf16 v[64:67], v[206:209], v[124:127], v[64:67]
	ds_read_b128 v[124:127], v146 offset:12288
	v_add_u32_e32 v146, v158, v154
	s_waitcnt lgkmcnt(2)
	v_mfma_f32_16x16x32_bf16 v[60:63], v[194:197], v[172:175], v[60:63]
	v_mfma_f32_16x16x32_bf16 v[56:59], v[198:201], v[172:175], v[56:59]
	v_mfma_f32_16x16x32_bf16 v[52:55], v[202:205], v[172:175], v[52:55]
	v_mfma_f32_16x16x32_bf16 v[48:51], v[206:209], v[172:175], v[48:51]
	ds_read_b128 v[172:175], v146
	s_waitcnt lgkmcnt(2)
	v_mfma_f32_16x16x32_bf16 v[44:47], v[194:197], v[0:3], v[44:47]
	v_mfma_f32_16x16x32_bf16 v[40:43], v[198:201], v[0:3], v[40:43]
	v_mfma_f32_16x16x32_bf16 v[36:39], v[202:205], v[0:3], v[36:39]
	v_mfma_f32_16x16x32_bf16 v[32:35], v[206:209], v[0:3], v[32:35]
	s_waitcnt lgkmcnt(1)
	v_mfma_f32_16x16x32_bf16 v[28:31], v[194:197], v[124:127], v[28:31]
	v_mfma_f32_16x16x32_bf16 v[24:27], v[198:201], v[124:127], v[24:27]
	v_mfma_f32_16x16x32_bf16 v[20:23], v[202:205], v[124:127], v[20:23]
	v_mfma_f32_16x16x32_bf16 v[16:19], v[206:209], v[124:127], v[16:19]
	s_waitcnt lgkmcnt(0)
	v_mfma_f32_16x16x32_bf16 v[12:15], v[194:197], v[172:175], v[12:15]
	v_mfma_f32_16x16x32_bf16 v[8:11], v[198:201], v[172:175], v[8:11]
	v_mfma_f32_16x16x32_bf16 v[0:3], v[202:205], v[172:175], v[4:7]
	v_mfma_f32_16x16x32_bf16 v[4:7], v[206:209], v[172:175], v[138:141]
	s_lshl_b32 s12, s42, 2
	s_mul_i32 s13, s42, 0xb000
	s_mul_hi_i32 s12, s12, 0x2c00
	s_add_u32 s43, s22, s13
	v_mov_b32_e32 v124, v142
	v_mov_b32_e32 v140, v133
	s_addc_u32 s44, s23, s12
	s_lshl_b32 s12, s40, 8
	s_waitcnt vmcnt(0)
	s_barrier
	s_ashr_i32 s13, s12, 31
	v_and_b32_e32 v162, 15, v124
	v_or_b32_e32 v125, v162, v145
	v_ashrrev_i32_e32 v124, 2, v124
	s_lshl_b64 s[12:13], s[12:13], 1
	v_mul_lo_u32 v125, v125, s3
	v_and_b32_e32 v124, -4, v124
	s_add_u32 s12, s43, s12
	v_add_u32_e32 v125, 0, v125
	v_add_lshl_u32 v126, v124, v132, 1
	s_addc_u32 s13, s44, s13
	v_lshlrev_b32_e32 v146, 1, v132
	v_lshl_add_u32 v161, v162, 2, v159
	v_add_u32_e32 v141, v125, v126
	v_lshl_add_u64 v[126:127], s[12:13], 0, v[146:147]
	v_ashrrev_i32_e32 v125, 31, v124
	v_lshl_add_u64 v[124:125], v[124:125], 1, v[126:127]
	ds_read_b32 v126, v161
	v_mul_u32_u24_e32 v127, 0x1600, v162
	v_cmp_gt_u32_e32 vcc, 2, v162
	v_lshlrev_b32_e32 v146, 1, v127
	v_lshl_add_u64 v[124:125], v[124:125], 0, v[146:147]
	s_waitcnt lgkmcnt(0)
	v_pk_mul_f32 v[138:139], v[164:165], v[126:127] op_sel_hi:[1,0]
	v_pk_mul_f32 v[164:165], v[166:167], v[126:127] op_sel_hi:[1,0]
	s_and_b64 s[12:13], s[8:9], vcc
	v_cvt_pk_bf16_f32 v138, v138, v139
	v_cvt_pk_bf16_f32 v139, v164, v165
	ds_write_b64 v141, v[138:139]
	s_and_saveexec_b64 s[44:45], s[12:13]
	s_cbranch_execz .LBB0_621
	flat_store_dwordx2 v[124:125], v[138:139]
